# first-SP fragment ds_reads of the peeled iteration hoisted above the unit header (LDS latency under the header SALU)
# baseline (speedup 1.0000x reference)
; #define PG8_STAGE(bufoff, gbase, voff) do { _Pragma("unroll") for (int _i = 0; _i < 2; ++_i) \
;         __builtin_amdgcn_global_load_lds((const unsigned*)((const char*)(gbase) + (voff)[_i]), (PG8_LAS unsigned*)(lds + (bufoff) + ldsw + _i * 8192), 16, 0, 0); } while (0)
; #define PG8_LDA(dst, b, h) do { _Pragma("unroll") for (int m = 0; m < 4; ++m) _Pragma("unroll") for (int k = 0; k < 2; ++k) dst[m][k] = *(const PG8_LAS bf16x8*)(lds + PG8_SA(b, h) + aoff + m * 2048 + k * 1024); } while (0)
; #define PG8_LDB(dst, b, h) do { _Pragma("unroll") for (int n = 0; n < 2; ++n) _Pragma("unroll") for (int k = 0; k < 2; ++k) dst[n][k] = *(const PG8_LAS bf16x8*)(lds + PG8_SB(b, h) + boff + n * 2048 + k * 1024); } while (0)
; #define PG8_SCHED __builtin_amdgcn_sched_barrier(0)
;     __host__ __device__ bool next(int i, Unit& u) const {
;         const long L = (long)i * G + c; if (L >= nwg) return false;
;         int wgid = (int)L; { const int q = nwg / NXCD, r = nwg % NXCD, xcd = wgid % NXCD, off = wgid / NXCD; wgid = (xcd < r ? xcd * (q + 1) : r * (q + 1) + (xcd - r) * q) + off; }
;         const int nig = WGM * nN, gid = wgid / nig, fm = gid * WGM, gsz = (nM - fm) < WGM ? (nM - fm) : WGM;
;         u.pm = fm + ((wgid % nig) % gsz); u.pn = (wgid % nig) / gsz; return true;
; template <class Epi, class Sched, bool ALIGN_EPI = false, bool SP2 = false>
; __device__ __forceinline__ void gemm_phase(PG8_LAS unsigned char* lds, const Gemm g, const Sched& S, const Epi& E) {
;     ...
;             PG8_LDB(B0, 0, 0); PG8_LDB(B1, 0, 1); PG8_SCHED; PG8_LDA(At, 0, 0); PG8_STAGE(PG8_SA(1, 1), a1 + hstepA, voffA);
.LBB0_499:
	v_add_u32_e32 v148, 0x10000, v195
	v_add_u32_e32 v164, 0x14000, v195
	ds_read_b128 v[136:139], v148
	ds_read_b128 v[140:143], v148 offset:1024
	ds_read_b128 v[144:147], v148 offset:2048
	ds_read_b128 v[148:151], v148 offset:3072
	ds_read_b128 v[152:155], v164
	ds_read_b128 v[156:159], v164 offset:1024
	ds_read_b128 v[160:163], v164 offset:2048
	ds_read_b128 v[164:167], v164 offset:3072
	ds_read_b128 v[168:171], v242
	ds_read_b128 v[172:175], v242 offset:1024
	ds_read_b128 v[176:179], v242 offset:2048
	ds_read_b128 v[200:203], v242 offset:3072
	ds_read_b128 v[204:207], v242 offset:4096
	ds_read_b128 v[208:211], v242 offset:5120
	ds_read_b128 v[212:215], v242 offset:6144
	ds_read_b128 v[244:247], v242 offset:7168
	s_add_i32 s43, s30, 1
	v_readlane_b32 s10, v254, 55
	s_mul_i32 s10, s43, s10
	s_mul_hi_u32 s11, s43, s90
	s_add_i32 s11, s11, s10
	s_mul_i32 s10, s43, s90
	s_add_u32 s10, s10, s91
	v_readlane_b32 s12, v254, 56
	s_addc_u32 s11, s11, s12
	v_readlane_b32 s12, v254, 32
	v_readlane_b32 s13, v254, 33
	s_nop 1
	v_mov_b64_e32 v[2:3], s[12:13]
	v_cmp_ge_i64_e32 vcc, s[10:11], v[2:3]
	v_cmp_lt_i64_e64 s[12:13], s[10:11], v[2:3]
	s_cbranch_vccnz .LBB0_501
	s_ashr_i32 s11, s10, 31
	s_lshr_b32 s11, s11, 29
	s_add_i32 s11, s10, s11
	s_ashr_i32 s16, s11, 3
	s_and_b32 s11, s11, -8
	s_sub_i32 s10, s10, s11
	s_lshr_b32 s11, s10, 31
	v_readlane_b32 s20, v254, 36
	s_or_b32 s11, s20, s11
	s_mul_i32 s10, s11, s10
	s_add_i32 s10, s10, s16
	s_ashr_i32 s11, s10, 31
	v_readlane_b32 s16, v254, 37
	s_xor_b32 s11, s11, s16
	s_abs_i32 s16, s10
	v_readlane_b32 s17, v254, 38
	s_mul_hi_u32 s17, s16, s17
	s_mul_i32 s18, s17, s49
	s_sub_i32 s16, s16, s18
	s_add_i32 s18, s17, 1
	s_sub_i32 s19, s16, s49
	s_cmp_ge_u32 s16, s49
	s_cselect_b32 s17, s18, s17
	s_cselect_b32 s16, s19, s16
	s_add_i32 s18, s17, 1
	s_cmp_ge_u32 s16, s49
	s_cselect_b32 s16, s18, s17
	s_xor_b32 s16, s16, s11
	s_sub_i32 s11, s16, s11
	s_lshl_b32 s16, s11, 3
	s_mul_i32 s11, s11, s20
	s_sub_i32 s10, s10, s11
	s_lshr_b32 s38, s10, 3
	s_and_b32 s10, s10, 7
	s_add_i32 s80, s10, s16

; #define PG8_STAGE(bufoff, gbase, voff) do { _Pragma("unroll") for (int _i = 0; _i < 2; ++_i) \
;         __builtin_amdgcn_global_load_lds((const unsigned*)((const char*)(gbase) + (voff)[_i]), (PG8_LAS unsigned*)(lds + (bufoff) + ldsw + _i * 8192), 16, 0, 0); } while (0)
; #define PG8_LDA(dst, b, h) do { _Pragma("unroll") for (int m = 0; m < 4; ++m) _Pragma("unroll") for (int k = 0; k < 2; ++k) dst[m][k] = *(const PG8_LAS bf16x8*)(lds + PG8_SA(b, h) + aoff + m * 2048 + k * 1024); } while (0)
; #define PG8_LDB(dst, b, h) do { _Pragma("unroll") for (int n = 0; n < 2; ++n) _Pragma("unroll") for (int k = 0; k < 2; ++k) dst[n][k] = *(const PG8_LAS bf16x8*)(lds + PG8_SB(b, h) + boff + n * 2048 + k * 1024); } while (0)
; #define PG8_MMA(ai, bj, At, Bt) do { __builtin_amdgcn_s_setprio(1); _Pragma("unroll") for (int m = 0; m < 4; ++m) _Pragma("unroll") for (int n = 0; n < 2; ++n) _Pragma("unroll") for (int k = 0; k < 2; ++k) \
;         acc[ai][bj][m][n] = __builtin_amdgcn_mfma_f32_16x16x32_bf16(Bt[n][k], At[m][k], acc[ai][bj][m][n], 0, 0, 0); __builtin_amdgcn_s_setprio(0); } while (0)
; #define PG8_WAIT_V(n) asm volatile("s_waitcnt vmcnt(" #n ")" ::: "memory")
; #define PG8_WAIT_L(n) asm volatile("s_waitcnt lgkmcnt(" #n ")" ::: "memory")
; template <class Epi, class Sched, bool ALIGN_EPI = false, bool SP2 = false>
; __device__ __forceinline__ void gemm_phase(PG8_LAS unsigned char* lds, const Gemm g, const Sched& S, const Epi& E) {
;     ...
;             const char* a1 = cA + (size_t)(t + 1) * kstepA;
;             const char* a2 = last ? nA : cA + (size_t)(t + 2) * kstepA; const char* b2 = last ? nB : cB + (size_t)(t + 2) * kstepB;
;             const char* a3 = a2 + kstepA; const char* b3 = b2 + kstepB;
;             if (last && has_next) { S.a_ready(nxt); E.prefetch(nxt, ui + 1, tid); }
;             if constexpr (SP2) {
;             PG8_LDB(B0, 0, 0); PG8_LDB(B1, 0, 1); PG8_SCHED; PG8_LDA(At, 0, 0); PG8_STAGE(PG8_SA(1, 1), a1 + hstepA, voffA);
;             PG8_WAIT_V(8); PG8_WAIT_L(0); PG8_BAR; PG8_MMA(0, 0, At, B0); PG8_MMA(0, 1, At, B1); PG8_BAR; PG8_SCHED;
;             PG8_LDA(At, 0, 1); PG8_STAGE(PG8_SB(0, 0), b2, voffB); PG8_STAGE(PG8_SB(0, 1), b2 + hstepB, voffB); PG8_STAGE(PG8_SA(0, 0), a2, voffA);
;             PG8_WAIT_V(8); PG8_WAIT_L(0); PG8_BAR; PG8_MMA(1, 0, At, B0); PG8_MMA(1, 1, At, B1); PG8_BAR; PG8_SCHED;
.LBB0_505:
	s_add_u32 s31, s2, s45
	s_addc_u32 s36, s3, s44
	s_lshl_b32 s16, s80, 8
	v_add_u32_e32 v2, s16, v1
	v_ashrrev_i32_e32 v3, 31, v2
	v_add_u32_e32 v4, s16, v232
	s_lshl_b32 s16, s43, 10
	v_lshlrev_b64 v[2:3], 7, v[2:3]
	v_ashrrev_i32_e32 v5, 31, v4
	s_and_b32 s16, s16, 0x400
	v_lshlrev_b64 v[4:5], 7, v[4:5]
	s_waitcnt lgkmcnt(0)
	v_lshl_add_u64 v[130:131], v[196:197], 0, v[2:3]
	s_add_u32 s39, s14, 0x10000
	v_add_u32_e32 v134, s16, v240
	v_lshl_add_u64 v[132:133], v[196:197], 0, v[4:5]
	v_add_u32_e32 v135, s16, v241
	s_addc_u32 s50, s15, 0
	s_mov_b64 s[14:15], 0
	s_mov_b64 s[16:17], 0
	s_add_u32 s18, s14, 1
	s_addc_u32 s19, s15, 0
	s_lshl_b64 s[60:61], s[18:19], s48
	s_add_u32 s14, s14, 2
	s_addc_u32 s15, s15, 0
	s_lshl_b64 s[18:19], s[14:15], s48
	s_add_u32 s18, s2, s18
	s_addc_u32 s19, s3, s19
	s_and_b64 s[16:17], s[16:17], exec
	s_cselect_b32 s24, s52, s18
	s_cselect_b32 s25, s53, s19
	s_cselect_b32 s19, s55, s50
	s_cselect_b32 s18, s54, s39
	s_add_u32 s16, s24, s35
	s_addc_u32 s17, s25, 0
	s_add_u32 s20, s18, 0x8000
	s_addc_u32 s21, s19, 0
	s_add_i32 s51, 0, 0x10000
	s_add_i32 s72, 0, 0x14000
	s_add_u32 s60, s31, s60
	s_addc_u32 s61, s36, s61
	v_lshl_add_u64 v[180:181], s[60:61], 0, v[184:185]
	s_add_i32 m0, s63, 0xc000
	global_load_lds_dwordx4 v[180:181], off
	v_lshl_add_u64 v[180:181], s[60:61], 0, v[188:189]
	s_add_i32 m0, s63, 0xe000
	s_nop 0
	global_load_lds_dwordx4 v[180:181], off
	s_waitcnt vmcnt(8)
	s_waitcnt lgkmcnt(0)
	s_barrier
	s_setprio 1
	s_waitcnt lgkmcnt(0)
	v_mfma_f32_16x16x32_bf16 v[126:129], v[136:139], v[168:171], 0
	v_mfma_f32_16x16x32_bf16 v[118:121], v[144:147], v[168:171], 0
	v_mfma_f32_16x16x32_bf16 v[110:113], v[136:139], v[176:179], 0
	v_mfma_f32_16x16x32_bf16 v[102:105], v[144:147], v[176:179], 0
	v_mfma_f32_16x16x32_bf16 v[94:97], v[136:139], v[204:207], 0
	v_mfma_f32_16x16x32_bf16 v[86:89], v[144:147], v[204:207], 0
	v_mfma_f32_16x16x32_bf16 v[78:81], v[136:139], v[212:215], 0
	v_mfma_f32_16x16x32_bf16 v[70:73], v[144:147], v[212:215], 0
	v_mfma_f32_16x16x32_bf16 v[126:129], v[140:143], v[172:175], v[126:129]
	v_mfma_f32_16x16x32_bf16 v[118:121], v[148:151], v[172:175], v[118:121]
	v_mfma_f32_16x16x32_bf16 v[110:113], v[140:143], v[200:203], v[110:113]
	v_mfma_f32_16x16x32_bf16 v[102:105], v[148:151], v[200:203], v[102:105]
	v_mfma_f32_16x16x32_bf16 v[94:97], v[140:143], v[208:211], v[94:97]
	v_mfma_f32_16x16x32_bf16 v[86:89], v[148:151], v[208:211], v[86:89]
	v_mfma_f32_16x16x32_bf16 v[78:81], v[140:143], v[244:247], v[78:81]
	v_mfma_f32_16x16x32_bf16 v[70:73], v[148:151], v[244:247], v[70:73]
	s_setprio 0
	s_setprio 1
	v_mfma_f32_16x16x32_bf16 v[122:125], v[152:155], v[168:171], 0
	v_mfma_f32_16x16x32_bf16 v[114:117], v[160:163], v[168:171], 0
	v_mfma_f32_16x16x32_bf16 v[106:109], v[152:155], v[176:179], 0
	v_mfma_f32_16x16x32_bf16 v[98:101], v[160:163], v[176:179], 0
	v_mfma_f32_16x16x32_bf16 v[90:93], v[152:155], v[204:207], 0
	v_mfma_f32_16x16x32_bf16 v[82:85], v[160:163], v[204:207], 0
	v_mfma_f32_16x16x32_bf16 v[74:77], v[152:155], v[212:215], 0
	v_mfma_f32_16x16x32_bf16 v[66:69], v[160:163], v[212:215], 0
	v_mfma_f32_16x16x32_bf16 v[122:125], v[156:159], v[172:175], v[122:125]
	v_mfma_f32_16x16x32_bf16 v[114:117], v[164:167], v[172:175], v[114:117]
	v_mfma_f32_16x16x32_bf16 v[106:109], v[156:159], v[200:203], v[106:109]
	v_mfma_f32_16x16x32_bf16 v[98:101], v[164:167], v[200:203], v[98:101]
	v_mfma_f32_16x16x32_bf16 v[90:93], v[156:159], v[208:211], v[90:93]
	v_mfma_f32_16x16x32_bf16 v[82:85], v[164:167], v[208:211], v[82:85]
	s_setprio 2
	s_barrier
	v_mfma_f32_16x16x32_bf16 v[74:77], v[156:159], v[244:247], v[74:77]
	v_mfma_f32_16x16x32_bf16 v[66:69], v[164:167], v[244:247], v[66:69]
	s_setprio 0
	s_add_i32 s51, s51, s62
	v_lshl_add_u64 v[180:181], s[18:19], 0, v[186:187]
	s_mov_b32 m0, s51
	ds_read_b128 v[168:171], v242 offset:16384
	ds_read_b128 v[172:175], v242 offset:17408
	ds_read_b128 v[176:179], v242 offset:18432
	ds_read_b128 v[200:203], v242 offset:19456
	ds_read_b128 v[204:207], v242 offset:20480
	ds_read_b128 v[208:211], v242 offset:21504
	ds_read_b128 v[212:215], v242 offset:22528
	ds_read_b128 v[244:247], v242 offset:23552
	global_load_lds_dwordx4 v[180:181], off
	s_add_i32 m0, s51, 0x2000
	s_add_u32 s60, s18, 0x4000
	v_lshl_add_u64 v[180:181], s[18:19], 0, v[190:191]
	s_addc_u32 s61, s19, 0
	s_add_i32 s51, s72, s62
	global_load_lds_dwordx4 v[180:181], off
	v_lshl_add_u64 v[180:181], s[60:61], 0, v[186:187]
	s_mov_b32 m0, s51
	s_nop 0
	global_load_lds_dwordx4 v[180:181], off
	v_lshl_add_u64 v[180:181], s[60:61], 0, v[190:191]
	s_add_i32 m0, s51, 0x2000
	s_nop 0
	global_load_lds_dwordx4 v[180:181], off
	v_lshl_add_u64 v[180:181], s[24:25], 0, v[184:185]
	s_mov_b32 m0, s63
	s_nop 0
	global_load_lds_dwordx4 v[180:181], off
	v_lshl_add_u64 v[180:181], s[24:25], 0, v[188:189]
	s_mov_b32 m0, s28
	s_nop 0
	global_load_lds_dwordx4 v[180:181], off
	s_waitcnt vmcnt(8)
	s_waitcnt lgkmcnt(0)
	s_barrier
; #define PG8_STAGE(bufoff, gbase, voff) do { _Pragma("unroll") for (int _i = 0; _i < 2; ++_i) \
;         __builtin_amdgcn_global_load_lds((const unsigned*)((const char*)(gbase) + (voff)[_i]), (PG8_LAS unsigned*)(lds + (bufoff) + ldsw + _i * 8192), 16, 0, 0); } while (0)
; #define PG8_LDA(dst, b, h) do { _Pragma("unroll") for (int m = 0; m < 4; ++m) _Pragma("unroll") for (int k = 0; k < 2; ++k) dst[m][k] = *(const PG8_LAS bf16x8*)(lds + PG8_SA(b, h) + aoff + m * 2048 + k * 1024); } while (0)
; #define PG8_LDB(dst, b, h) do { _Pragma("unroll") for (int n = 0; n < 2; ++n) _Pragma("unroll") for (int k = 0; k < 2; ++k) dst[n][k] = *(const PG8_LAS bf16x8*)(lds + PG8_SB(b, h) + boff + n * 2048 + k * 1024); } while (0)
; #define PG8_MMA(ai, bj, At, Bt) do { __builtin_amdgcn_s_setprio(1); _Pragma("unroll") for (int m = 0; m < 4; ++m) _Pragma("unroll") for (int n = 0; n < 2; ++n) _Pragma("unroll") for (int k = 0; k < 2; ++k) \
;         acc[ai][bj][m][n] = __builtin_amdgcn_mfma_f32_16x16x32_bf16(Bt[n][k], At[m][k], acc[ai][bj][m][n], 0, 0, 0); __builtin_amdgcn_s_setprio(0); } while (0)
; #define PG8_WAIT_V(n) asm volatile("s_waitcnt vmcnt(" #n ")" ::: "memory")
; #define PG8_WAIT_L(n) asm volatile("s_waitcnt lgkmcnt(" #n ")" ::: "memory")
; #define PG8_BAR __builtin_amdgcn_s_barrier()
; #define PG8_SCHED __builtin_amdgcn_sched_barrier(0)
; template <class Epi, class Sched, bool ALIGN_EPI = false, bool SP2 = false>
; __device__ __forceinline__ void gemm_phase(PG8_LAS unsigned char* lds, const Gemm g, const Sched& S, const Epi& E) {
;     ...
;             PG8_WAIT_V(8); PG8_WAIT_L(0); PG8_BAR; PG8_MMA(1, 0, At, B0); PG8_MMA(1, 1, At, B1); PG8_BAR; PG8_SCHED;
;             PG8_LDB(B0, 1, 0); PG8_LDB(B1, 1, 1); PG8_SCHED; PG8_LDA(At, 1, 0); PG8_STAGE(PG8_SA(0, 1), a2 + hstepA, voffA);
;             PG8_WAIT_V(8); PG8_WAIT_L(0); PG8_BAR; PG8_MMA(0, 0, At, B0); PG8_MMA(0, 1, At, B1); PG8_BAR; PG8_SCHED;
	s_setprio 1
	s_waitcnt lgkmcnt(0)
	v_mfma_f32_16x16x32_bf16 v[62:65], v[136:139], v[168:171], 0
	v_mfma_f32_16x16x32_bf16 v[54:57], v[144:147], v[168:171], 0
	v_mfma_f32_16x16x32_bf16 v[46:49], v[136:139], v[176:179], 0
	v_mfma_f32_16x16x32_bf16 v[38:41], v[144:147], v[176:179], 0
	v_mfma_f32_16x16x32_bf16 v[30:33], v[136:139], v[204:207], 0
	v_mfma_f32_16x16x32_bf16 v[22:25], v[144:147], v[204:207], 0
	v_mfma_f32_16x16x32_bf16 v[14:17], v[136:139], v[212:215], 0
	v_mfma_f32_16x16x32_bf16 v[6:9], v[144:147], v[212:215], 0
	v_mfma_f32_16x16x32_bf16 v[62:65], v[140:143], v[172:175], v[62:65]
	v_mfma_f32_16x16x32_bf16 v[54:57], v[148:151], v[172:175], v[54:57]
	v_mfma_f32_16x16x32_bf16 v[46:49], v[140:143], v[200:203], v[46:49]
	v_mfma_f32_16x16x32_bf16 v[38:41], v[148:151], v[200:203], v[38:41]
	v_mfma_f32_16x16x32_bf16 v[30:33], v[140:143], v[208:211], v[30:33]
	v_mfma_f32_16x16x32_bf16 v[22:25], v[148:151], v[208:211], v[22:25]
	v_mfma_f32_16x16x32_bf16 v[14:17], v[140:143], v[244:247], v[14:17]
	v_mfma_f32_16x16x32_bf16 v[6:9], v[148:151], v[244:247], v[6:9]
	s_setprio 0
	s_setprio 1
	v_mfma_f32_16x16x32_bf16 v[58:61], v[152:155], v[168:171], 0
	v_mfma_f32_16x16x32_bf16 v[50:53], v[160:163], v[168:171], 0
	v_mfma_f32_16x16x32_bf16 v[42:45], v[152:155], v[176:179], 0
	v_mfma_f32_16x16x32_bf16 v[34:37], v[160:163], v[176:179], 0
	v_mfma_f32_16x16x32_bf16 v[26:29], v[152:155], v[204:207], 0
	v_mfma_f32_16x16x32_bf16 v[18:21], v[160:163], v[204:207], 0
	v_mfma_f32_16x16x32_bf16 v[10:13], v[152:155], v[212:215], 0
	v_mfma_f32_16x16x32_bf16 v[2:5], v[160:163], v[212:215], 0
	v_mfma_f32_16x16x32_bf16 v[58:61], v[156:159], v[172:175], v[58:61]
	v_mfma_f32_16x16x32_bf16 v[50:53], v[164:167], v[172:175], v[50:53]
	v_mfma_f32_16x16x32_bf16 v[42:45], v[156:159], v[200:203], v[42:45]
	v_mfma_f32_16x16x32_bf16 v[34:37], v[164:167], v[200:203], v[34:37]
	v_mfma_f32_16x16x32_bf16 v[26:29], v[156:159], v[208:211], v[26:29]
	v_mfma_f32_16x16x32_bf16 v[18:21], v[164:167], v[208:211], v[18:21]
	s_setprio 2
	s_barrier
	v_mfma_f32_16x16x32_bf16 v[10:13], v[156:159], v[244:247], v[10:13]
	v_mfma_f32_16x16x32_bf16 v[2:5], v[164:167], v[244:247], v[2:5]
	s_setprio 0
	s_add_i32 s51, 0, 0x18000
	s_add_i32 s60, 0, 0x1c000
	v_add_u32_e32 v148, s51, v195
	v_add_u32_e32 v164, s60, v195
	ds_read_b128 v[136:139], v148
	ds_read_b128 v[140:143], v148 offset:1024
	ds_read_b128 v[144:147], v148 offset:2048
	ds_read_b128 v[148:151], v148 offset:3072
	ds_read_b128 v[152:155], v164
	ds_read_b128 v[156:159], v164 offset:1024
	ds_read_b128 v[160:163], v164 offset:2048
	ds_read_b128 v[164:167], v164 offset:3072
	s_add_u32 s24, s24, s45
	s_addc_u32 s25, s25, s44
	s_mov_b32 m0, s29
	v_lshl_add_u64 v[180:181], s[24:25], 0, v[184:185]
	ds_read_b128 v[168:171], v242 offset:32768
	ds_read_b128 v[172:175], v242 offset:33792
	ds_read_b128 v[176:179], v242 offset:34816
	ds_read_b128 v[200:203], v242 offset:35840
	ds_read_b128 v[204:207], v242 offset:36864
	ds_read_b128 v[208:211], v242 offset:37888
	ds_read_b128 v[212:215], v242 offset:38912
	ds_read_b128 v[244:247], v242 offset:39936
	global_load_lds_dwordx4 v[180:181], off
	v_lshl_add_u64 v[180:181], s[24:25], 0, v[188:189]
	s_mov_b32 m0, s26
	s_nop 0
	global_load_lds_dwordx4 v[180:181], off
	s_waitcnt vmcnt(8)
	s_waitcnt lgkmcnt(0)
	s_barrier
	s_setprio 1
	s_waitcnt lgkmcnt(0)
	v_mfma_f32_16x16x32_bf16 v[126:129], v[136:139], v[168:171], v[126:129]
	v_mfma_f32_16x16x32_bf16 v[118:121], v[144:147], v[168:171], v[118:121]
	v_mfma_f32_16x16x32_bf16 v[110:113], v[136:139], v[176:179], v[110:113]
	v_mfma_f32_16x16x32_bf16 v[102:105], v[144:147], v[176:179], v[102:105]
	v_mfma_f32_16x16x32_bf16 v[94:97], v[136:139], v[204:207], v[94:97]
	v_mfma_f32_16x16x32_bf16 v[86:89], v[144:147], v[204:207], v[86:89]
	v_mfma_f32_16x16x32_bf16 v[78:81], v[136:139], v[212:215], v[78:81]
	v_mfma_f32_16x16x32_bf16 v[70:73], v[144:147], v[212:215], v[70:73]
	v_mfma_f32_16x16x32_bf16 v[126:129], v[140:143], v[172:175], v[126:129]
	v_mfma_f32_16x16x32_bf16 v[118:121], v[148:151], v[172:175], v[118:121]
	v_mfma_f32_16x16x32_bf16 v[110:113], v[140:143], v[200:203], v[110:113]
	v_mfma_f32_16x16x32_bf16 v[102:105], v[148:151], v[200:203], v[102:105]
	v_mfma_f32_16x16x32_bf16 v[94:97], v[140:143], v[208:211], v[94:97]
	v_mfma_f32_16x16x32_bf16 v[86:89], v[148:151], v[208:211], v[86:89]
	v_mfma_f32_16x16x32_bf16 v[78:81], v[140:143], v[244:247], v[78:81]
	v_mfma_f32_16x16x32_bf16 v[70:73], v[148:151], v[244:247], v[70:73]
	s_setprio 0
	s_setprio 1
	v_mfma_f32_16x16x32_bf16 v[122:125], v[152:155], v[168:171], v[122:125]
	v_mfma_f32_16x16x32_bf16 v[114:117], v[160:163], v[168:171], v[114:117]
	v_mfma_f32_16x16x32_bf16 v[106:109], v[152:155], v[176:179], v[106:109]
	v_mfma_f32_16x16x32_bf16 v[98:101], v[160:163], v[176:179], v[98:101]
	v_mfma_f32_16x16x32_bf16 v[90:93], v[152:155], v[204:207], v[90:93]
	v_mfma_f32_16x16x32_bf16 v[82:85], v[160:163], v[204:207], v[82:85]
	v_mfma_f32_16x16x32_bf16 v[74:77], v[152:155], v[212:215], v[74:77]
	v_mfma_f32_16x16x32_bf16 v[66:69], v[160:163], v[212:215], v[66:69]
	v_mfma_f32_16x16x32_bf16 v[122:125], v[156:159], v[172:175], v[122:125]
	v_mfma_f32_16x16x32_bf16 v[114:117], v[164:167], v[172:175], v[114:117]
	v_mfma_f32_16x16x32_bf16 v[106:109], v[156:159], v[200:203], v[106:109]
	v_mfma_f32_16x16x32_bf16 v[98:101], v[164:167], v[200:203], v[98:101]
	v_mfma_f32_16x16x32_bf16 v[90:93], v[156:159], v[208:211], v[90:93]
	v_mfma_f32_16x16x32_bf16 v[82:85], v[164:167], v[208:211], v[82:85]
	s_setprio 2
	s_barrier
; #define PG8_STAGE(bufoff, gbase, voff) do { _Pragma("unroll") for (int _i = 0; _i < 2; ++_i) \
;         __builtin_amdgcn_global_load_lds((const unsigned*)((const char*)(gbase) + (voff)[_i]), (PG8_LAS unsigned*)(lds + (bufoff) + ldsw + _i * 8192), 16, 0, 0); } while (0)
; #define PG8_LDA(dst, b, h) do { _Pragma("unroll") for (int m = 0; m < 4; ++m) _Pragma("unroll") for (int k = 0; k < 2; ++k) dst[m][k] = *(const PG8_LAS bf16x8*)(lds + PG8_SA(b, h) + aoff + m * 2048 + k * 1024); } while (0)
; #define PG8_MMA(ai, bj, At, Bt) do { __builtin_amdgcn_s_setprio(1); _Pragma("unroll") for (int m = 0; m < 4; ++m) _Pragma("unroll") for (int n = 0; n < 2; ++n) _Pragma("unroll") for (int k = 0; k < 2; ++k) \
;         acc[ai][bj][m][n] = __builtin_amdgcn_mfma_f32_16x16x32_bf16(Bt[n][k], At[m][k], acc[ai][bj][m][n], 0, 0, 0); __builtin_amdgcn_s_setprio(0); } while (0)
; #define PG8_WAIT_V(n) asm volatile("s_waitcnt vmcnt(" #n ")" ::: "memory")
; #define PG8_WAIT_L(n) asm volatile("s_waitcnt lgkmcnt(" #n ")" ::: "memory")
; #define PG8_BAR __builtin_amdgcn_s_barrier()
; #define PG8_SCHED __builtin_amdgcn_sched_barrier(0)
; template <class Epi, class Sched, bool ALIGN_EPI = false, bool SP2 = false>
; __device__ __forceinline__ void gemm_phase(PG8_LAS unsigned char* lds, const Gemm g, const Sched& S, const Epi& E) {
;     ...
;             PG8_LDA(At, 1, 1); PG8_STAGE(PG8_SB(1, 0), b3, voffB); PG8_STAGE(PG8_SB(1, 1), b3 + hstepB, voffB); PG8_STAGE(PG8_SA(1, 0), a3, voffA);
;             PG8_WAIT_V(8); PG8_WAIT_L(0); PG8_BAR; PG8_MMA(1, 0, At, B0); PG8_MMA(1, 1, At, B1); PG8_BAR; PG8_SCHED;
	v_mfma_f32_16x16x32_bf16 v[74:77], v[156:159], v[244:247], v[74:77]
	v_mfma_f32_16x16x32_bf16 v[66:69], v[164:167], v[244:247], v[66:69]
	s_setprio 0
	s_add_i32 s24, s51, s62
	v_lshl_add_u64 v[180:181], s[20:21], 0, v[186:187]
	s_mov_b32 m0, s24
	ds_read_b128 v[168:171], v242 offset:49152
	ds_read_b128 v[172:175], v242 offset:50176
	ds_read_b128 v[176:179], v242 offset:51200
	ds_read_b128 v[200:203], v242 offset:52224
	ds_read_b128 v[204:207], v242 offset:53248
	ds_read_b128 v[208:211], v242 offset:54272
	ds_read_b128 v[212:215], v242 offset:55296
	ds_read_b128 v[244:247], v242 offset:56320
	global_load_lds_dwordx4 v[180:181], off
	s_add_i32 m0, s24, 0x2000
	s_add_u32 s18, s18, 0xc000
	v_lshl_add_u64 v[180:181], s[20:21], 0, v[190:191]
	s_addc_u32 s19, s19, 0
	s_add_i32 s20, s60, s62
	global_load_lds_dwordx4 v[180:181], off
	v_lshl_add_u64 v[180:181], s[18:19], 0, v[186:187]
	s_mov_b32 m0, s20
	s_nop 0
	global_load_lds_dwordx4 v[180:181], off
	v_lshl_add_u64 v[180:181], s[18:19], 0, v[190:191]
	s_add_i32 m0, s20, 0x2000
	s_nop 0
	global_load_lds_dwordx4 v[180:181], off
	v_lshl_add_u64 v[180:181], s[16:17], 0, v[184:185]
	s_mov_b32 m0, s1
	s_nop 0
	global_load_lds_dwordx4 v[180:181], off
	v_lshl_add_u64 v[180:181], s[16:17], 0, v[188:189]
	s_mov_b32 m0, s0
	s_nop 0
	global_load_lds_dwordx4 v[180:181], off
	s_waitcnt vmcnt(8)
	s_waitcnt lgkmcnt(0)
	s_barrier
	s_setprio 1
	s_waitcnt lgkmcnt(0)
	v_mfma_f32_16x16x32_bf16 v[62:65], v[136:139], v[168:171], v[62:65]
	v_mfma_f32_16x16x32_bf16 v[54:57], v[144:147], v[168:171], v[54:57]
	v_mfma_f32_16x16x32_bf16 v[46:49], v[136:139], v[176:179], v[46:49]
	v_mfma_f32_16x16x32_bf16 v[38:41], v[144:147], v[176:179], v[38:41]
	v_mfma_f32_16x16x32_bf16 v[30:33], v[136:139], v[204:207], v[30:33]
	v_mfma_f32_16x16x32_bf16 v[22:25], v[144:147], v[204:207], v[22:25]
	v_mfma_f32_16x16x32_bf16 v[14:17], v[136:139], v[212:215], v[14:17]
	v_mfma_f32_16x16x32_bf16 v[6:9], v[144:147], v[212:215], v[6:9]
	v_mfma_f32_16x16x32_bf16 v[62:65], v[140:143], v[172:175], v[62:65]
	v_mfma_f32_16x16x32_bf16 v[54:57], v[148:151], v[172:175], v[54:57]
	v_mfma_f32_16x16x32_bf16 v[46:49], v[140:143], v[200:203], v[46:49]
	v_mfma_f32_16x16x32_bf16 v[38:41], v[148:151], v[200:203], v[38:41]
	v_mfma_f32_16x16x32_bf16 v[30:33], v[140:143], v[208:211], v[30:33]
	v_mfma_f32_16x16x32_bf16 v[22:25], v[148:151], v[208:211], v[22:25]
	v_mfma_f32_16x16x32_bf16 v[14:17], v[140:143], v[244:247], v[14:17]
	v_mfma_f32_16x16x32_bf16 v[6:9], v[148:151], v[244:247], v[6:9]
	s_setprio 0
	s_setprio 1
	v_mfma_f32_16x16x32_bf16 v[58:61], v[152:155], v[168:171], v[58:61]
	v_mfma_f32_16x16x32_bf16 v[50:53], v[160:163], v[168:171], v[50:53]
	v_mfma_f32_16x16x32_bf16 v[42:45], v[152:155], v[176:179], v[42:45]
	v_mfma_f32_16x16x32_bf16 v[34:37], v[160:163], v[176:179], v[34:37]
	v_mfma_f32_16x16x32_bf16 v[26:29], v[152:155], v[204:207], v[26:29]
	v_mfma_f32_16x16x32_bf16 v[18:21], v[160:163], v[204:207], v[18:21]
	v_mfma_f32_16x16x32_bf16 v[10:13], v[152:155], v[212:215], v[10:13]
	v_mfma_f32_16x16x32_bf16 v[2:5], v[160:163], v[212:215], v[2:5]
	v_mfma_f32_16x16x32_bf16 v[58:61], v[156:159], v[172:175], v[58:61]
	v_mfma_f32_16x16x32_bf16 v[50:53], v[164:167], v[172:175], v[50:53]
	v_mfma_f32_16x16x32_bf16 v[42:45], v[156:159], v[200:203], v[42:45]
	v_mfma_f32_16x16x32_bf16 v[34:37], v[164:167], v[200:203], v[34:37]
	v_mfma_f32_16x16x32_bf16 v[26:29], v[156:159], v[208:211], v[26:29]
	v_mfma_f32_16x16x32_bf16 v[18:21], v[164:167], v[208:211], v[18:21]
	s_setprio 2
	s_barrier
	v_mfma_f32_16x16x32_bf16 v[10:13], v[156:159], v[244:247], v[10:13]
	v_mfma_f32_16x16x32_bf16 v[2:5], v[164:167], v[244:247], v[2:5]
	s_setprio 0
	s_add_u32 s39, s39, 0x10000
	s_addc_u32 s50, s50, 0
	s_branch .LBB0_508
